# NSA selected pass: K/V staging global loads keep one extra iteration in flight (counted vmcnt 7..4 when next tile prefetch was issued)
# speedup vs baseline: 1.0005x; 1.0002x over previous
; template <int MODE> ...
;     ...
;     if (kb + 2 <= kb1) stage_load<NEEDV>(sr2, K, VT, ldvt, kb + 2, tid);
;     body(kb, buf0, buf0 + KS_BYTES);
;     if (kb < kb1) stage_store<NEEDV>(sr, buf1, buf1 + KS_BYTES, tid);
;     __syncthreads();
;     if (++kb > kb1) break;
;     if (kb + 2 <= kb1) stage_load<NEEDV>(sr, K, VT, ldvt, kb + 2, tid);
;     body(kb, buf1, buf1 + KS_BYTES);
;     if (kb < kb1) stage_store<NEEDV>(sr2, buf0, buf0 + KS_BYTES, tid);
;     __syncthreads();
.LBB0_169:
	s_cmp_gt_u32 s14, s12
	s_cbranch_scc0 .Lrelax_m2a
	s_waitcnt vmcnt(3)
	ds_write_b128 v182, v[118:121]
	s_waitcnt vmcnt(2)
	ds_write_b128 v183, v[122:125]
	s_waitcnt vmcnt(1)
	ds_write_b128 v189, v[126:129]
	s_waitcnt vmcnt(0)
	ds_write_b128 v190, v[130:133]
	s_branch .Lrelax_m2a_join
.Lrelax_m2a:
	s_waitcnt vmcnt(7)
	ds_write_b128 v182, v[118:121]
	s_waitcnt vmcnt(6)
	ds_write_b128 v183, v[122:125]
	s_waitcnt vmcnt(5)
	ds_write_b128 v189, v[126:129]
	s_waitcnt vmcnt(4)
	ds_write_b128 v190, v[130:133]
.Lrelax_m2a_join:
.LBB0_170:
	s_andn2_b64 vcc, exec, s[0:1]
	s_mov_b64 s[0:1], -1
	s_waitcnt lgkmcnt(0)
	s_barrier
	s_cbranch_vccnz .LBB0_160
	s_cmp_gt_u32 s13, s12
	s_cbranch_scc1 .LBB0_173
	s_mov_b32 s11, s19
	s_lshl_b64 s[0:1], s[10:11], 1
	v_lshl_add_u64 v[66:67], v[168:169], 0, s[0:1]
	v_lshl_add_u64 v[68:69], v[170:171], 0, s[0:1]
	global_load_dwordx4 v[118:121], v[172:173], off
	global_load_dwordx4 v[122:125], v[174:175], off
	global_load_dwordx4 v[126:129], v[66:67], off
	global_load_dwordx4 v[130:133], v[68:69], off

; template <int MODE> ...
;     ...
;     if (kb + 2 <= kb1) stage_load<NEEDV>(sr2, K, VT, ldvt, kb + 2, tid);
;     body(kb, buf0, buf0 + KS_BYTES);
;     if (kb < kb1) stage_store<NEEDV>(sr, buf1, buf1 + KS_BYTES, tid);
;     __syncthreads();
;     if (++kb > kb1) break;
;     if (kb + 2 <= kb1) stage_load<NEEDV>(sr, K, VT, ldvt, kb + 2, tid);
;     body(kb, buf1, buf1 + KS_BYTES);
;     if (kb < kb1) stage_store<NEEDV>(sr2, buf0, buf0 + KS_BYTES, tid);
;     __syncthreads();
.LBB0_179:
	s_cmp_gt_u32 s13, s12
	s_cbranch_scc0 .Lrelax_m2b
	s_waitcnt vmcnt(3)
	ds_write_b128 v178, v[134:137]
	s_waitcnt vmcnt(2)
	ds_write_b128 v179, v[138:141]
	s_waitcnt vmcnt(1)
	ds_write_b128 v184, v[142:145]
	s_waitcnt vmcnt(0)
	ds_write_b128 v185, v[146:149]
	s_branch .Lrelax_m2b_join
.Lrelax_m2b:
	s_waitcnt vmcnt(7)
	ds_write_b128 v178, v[134:137]
	s_waitcnt vmcnt(6)
	ds_write_b128 v179, v[138:141]
	s_waitcnt vmcnt(5)
	ds_write_b128 v184, v[142:145]
	s_waitcnt vmcnt(4)
	ds_write_b128 v185, v[146:149]
.Lrelax_m2b_join:
.LBB0_180:
	s_addk_i32 s10, 0x80
	s_add_i32 s13, s13, 2
	s_cmp_gt_u32 s14, s12
	v_lshl_add_u64 v[172:173], v[172:173], 0, s[0:1]
	v_lshl_add_u64 v[174:175], v[174:175], 0, s[0:1]
	s_cselect_b64 s[0:1], -1, 0
	s_waitcnt lgkmcnt(0)
	s_barrier
	s_and_b64 vcc, exec, s[0:1]
	s_cbranch_vccz .LBB0_161
	s_branch .LBB0_183
